# final3 + half-workgroup stagger: waves 4-7 run rotated key-step loop (exp/PV half deferred past the barrier) in both FoX and band units
# baseline (speedup 1.0000x reference)
; #define LAS __attribute__((address_space(3)))
; __device__ __forceinline__ unsigned v_lane_off(int lane) { return (unsigned)((4 * (lane >> 5) + ((lane & 15) >> 2)) * 64 + ((lane >> 4) & 1) * 32 + (lane & 3) * 8); }
; template <int MODE> ...
;     ...
;     const int r32 = lane & 31, hi = lane >> 5;
;     const int w = __builtin_amdgcn_readfirstlane(tid >> 6);
;     bf16x8 qf[4];
; #pragma unroll
;     for (int d0 = 0; d0 < 4; ++d0) qf[d0] = *(const bf16x8*)(Qrow + r32 * 64 + d0 * 16 + hi * 8);
;     const int kkey = 8 * w + (lane >> 3), kch = (lane & 7) ^ ((kkey >> 1) & 7);
;     const int vkey = 8 * w + ((lane >> 2) & 7), vch = 4 * ((lane >> 5) & 1) + (lane & 3);
;     const bf16_t* kg = Kb + kkey * 64 + kch * 8;
;     const bf16_t* vg = Vb + vkey * 64 + vch * 8;
;     const unsigned ring0 = (unsigned)(unsigned long)ring;
;     const unsigned kdst = (unsigned)__builtin_amdgcn_readfirstlane(ring0 + w * 1024), vdst = kdst + 8192;
;     const float cq = (MODE == 1) ? tab[qpos0 + r32] : 0.f;
;     const float cfar = (MODE == 0) ? tab[256] : 0.f;
;     const unsigned vl = v_lane_off(lane);
;     St S; st_init(S);
;     asm volatile("" :: "v"(qf[0]), "v"(qf[1]), "v"(qf[2]), "v"(qf[3]));
;     constexpr bool REV = (MODE == 1);
;     ...
;     int s0 = 0, s1 = 16384, s2 = 32768;
;     glds16(kg + (size_t)SU_T(T0) * 4096, kdst + s0); glds16(vg + (size_t)SU_T(T0) * 4096, vdst + s0);
;     if (T0 + 1 < T1) { glds16(kg + (size_t)SU_T(T0 + 1) * 4096, kdst + s1); glds16(vg + (size_t)SU_T(T0 + 1) * 4096, vdst + s1);
;                        asm volatile("s_waitcnt vmcnt(2) lgkmcnt(0)\n\ts_barrier" ::: "memory"); }
;     else             { asm volatile("s_waitcnt vmcnt(0) lgkmcnt(0)\n\ts_barrier" ::: "memory"); }
;     for (int s = T0; s < T1; ++s) {
;         const int t = SU_T(s);
;         const bool more = (s + 2 < T1);
;         if (more) { glds16(kg + (size_t)SU_T(s + 2) * 4096, kdst + s2); glds16(vg + (size_t)SU_T(s + 2) * 4096, vdst + s2); }
;         LAS unsigned char* buf = ring + s0;
;         if (t >= t_lo && t < t_hi)
;             step64<MODE>(S, qf, t, qpos0, t == t_hi - 1, REV ? (t == t_hi - 1) : (t == t_lo), cq, cfar, tab, buf, (unsigned)(unsigned long)(buf + 8192) + vl, r32, hi);
.LBB0_603:
	s_mov_b64 s[0:1], -1
	s_cmp_le_u32 s44, s3
	v_lshrrev_b32_e32 v147, 1, v143
	s_cbranch_scc0 .LBB0_631
	v_and_b32_e32 v8, 63, v143
	v_lshrrev_b32_e32 v9, 3, v143
	v_and_b32_e32 v7, 3, v7
	v_and_or_b32 v7, v9, 4, v7
	v_lshlrev_b32_e32 v9, 1, v8
	v_lshlrev_b32_e32 v8, 3, v8
	v_lshlrev_b32_e32 v7, 6, v7
	v_and_b32_e32 v9, 32, v9
	v_and_b32_e32 v8, 24, v8
	s_lshl_b32 s0, s2, 8
	v_lshrrev_b32_e32 v146, 1, v143
	v_readlane_b32 s1, v240, 12
	v_or3_b32 v151, v8, v9, v7
	v_bfe_u32 v7, v143, 1, 3
	v_bitop3_b32 v8, v6, v146, 7 bitop3:0x78
	s_add_i32 s0, s1, s0
	s_lshl_b32 s1, s44, 6
	s_mov_b32 s45, s13
	v_lshl_or_b32 v152, v8, 4, v0
	v_bitop3_b32 v8, v6, v7, 2 bitop3:0x36
	s_sub_i32 s48, s0, s1
	s_lshl_b64 s[0:1], s[44:45], 13
	v_lshl_or_b32 v153, v8, 4, v0
	v_bitop3_b32 v8, v6, v7, 4 bitop3:0x36
	v_bitop3_b32 v7, v6, v7, 6 bitop3:0x36
	v_lshl_add_u64 v[4:5], v[4:5], 0, s[0:1]
	s_mov_b64 s[2:3], 0x4000
	v_lshl_add_u64 v[2:3], v[2:3], 0, s[0:1]
	v_mov_b32_e32 v14, v1
	v_mov_b32_e32 v15, v1
	s_lshr_b32 s41, s40, 1
	v_lshl_or_b32 v154, v8, 4, v0
	v_lshl_or_b32 v155, v7, 4, v0
	v_mad_i32_i24 v156, v6, -4, v144
	v_lshl_add_u64 v[122:123], v[4:5], 0, s[2:3]
	v_lshl_add_u64 v[124:125], v[2:3], 0, s[2:3]
	v_mov_b32_e32 v0, v1
	v_mov_b32_e32 v2, v1
	v_mov_b32_e32 v3, v1
	v_mov_b32_e32 v4, v1
	v_mov_b32_e32 v5, v1
	v_mov_b32_e32 v6, v1
	v_mov_b32_e32 v7, v1
	v_mov_b32_e32 v8, v1
	v_mov_b32_e32 v9, v1
	v_mov_b32_e32 v10, v1
	v_mov_b32_e32 v11, v1
	v_mov_b32_e32 v12, v1
	v_mov_b32_e32 v13, v1
	v_mov_b64_e32 v[30:31], v[14:15]
	v_mov_b64_e32 v[46:47], v[14:15]
	v_sub_u32_e64 v148, s41, 8 clamp
	v_sub_u32_e64 v149, s6, 8 clamp
	s_mov_b32 s0, 0
	v_mov_b32_e32 v157, 0
	s_mov_b32 s49, 0x8000
	s_movk_i32 s45, 0x4000
	v_mov_b32_e32 v150, 0
	v_mov_b64_e32 v[28:29], v[12:13]
	v_mov_b64_e32 v[26:27], v[10:11]
	v_mov_b64_e32 v[24:25], v[8:9]
	v_mov_b64_e32 v[22:23], v[6:7]
	v_mov_b64_e32 v[20:21], v[4:5]
	v_mov_b64_e32 v[18:19], v[2:3]
	v_mov_b64_e32 v[16:17], v[0:1]
	v_mov_b64_e32 v[44:45], v[12:13]
	v_mov_b64_e32 v[42:43], v[10:11]
	v_mov_b64_e32 v[40:41], v[8:9]
	v_mov_b64_e32 v[38:39], v[6:7]
	v_mov_b64_e32 v[36:37], v[4:5]
	v_mov_b64_e32 v[34:35], v[2:3]
	v_mov_b64_e32 v[32:33], v[0:1]
	v_bfe_u32 v239, v143, 5, 1
	v_lshlrev_b32_e32 v239, 2, v239
	v_sub_u32_e32 v239, v239, v144
	v_sub_u32_e32 v238, 0, v144
	v_and_b32_e32 v238, 3, v238
	v_sub_u32_e32 v239, v239, v238
	v_add_u32_e32 v239, 224, v239
	v_lshlrev_b32_e32 v239, 2, v239
	v_mul_u32_u24_e32 v238, 1184, v238
	v_add_u32_e32 v238, v238, v239
	v_add_u32_e32 v238, 137216, v238
	s_cmp_ge_u32 s86, 4
	s_cbranch_scc1 .Lr0_top

; template <int MODE>
; __device__ __forceinline__ void step64(St& S, const bf16x8 (&qf)[4], int t, int qpos0, bool diag, bool first, float cq, float cfar, const LAS float* tab,
;                                        const LAS unsigned char* buf, unsigned vaddr, int r32, int hi) {
;     ...
; #pragma unroll
;     for (int r = 0; r < 16; ++r) { sa[r] = __builtin_amdgcn_exp2f(sa[r]); sb[r] = __builtin_amdgcn_exp2f(sb[r]); }
;     asm volatile("s_waitcnt lgkmcnt(0)" ::: "memory");
;     __builtin_amdgcn_sched_barrier(0);
;     u32x4 pa0, pa1, pb0, pb1;
;     pa0.x = pk2(sa[0], sa[1]); pa0.y = pk2(sa[2], sa[3]); pa0.z = pk2(sa[4], sa[5]); pa0.w = pk2(sa[6], sa[7]);
;     pa1.x = pk2(sa[8], sa[9]); pa1.y = pk2(sa[10], sa[11]); pa1.z = pk2(sa[12], sa[13]); pa1.w = pk2(sa[14], sa[15]);
;     pb0.x = pk2(sb[0], sb[1]); pb0.y = pk2(sb[2], sb[3]); pb0.z = pk2(sb[4], sb[5]); pb0.w = pk2(sb[6], sb[7]);
;     pb1.x = pk2(sb[8], sb[9]); pb1.y = pk2(sb[10], sb[11]); pb1.z = pk2(sb[12], sb[13]); pb1.w = pk2(sb[14], sb[15]);
;     ...
;     S.o0 = __builtin_amdgcn_mfma_f32_32x32x16_bf16(ATT_VF(0), ATT_PF(pa0), S.o0, 0, 0, 0);
;     S.o1 = __builtin_amdgcn_mfma_f32_32x32x16_bf16(ATT_VF(2), ATT_PF(pa0), S.o1, 0, 0, 0);
;     S.o0 = __builtin_amdgcn_mfma_f32_32x32x16_bf16(ATT_VF(1), ATT_PF(pa1), S.o0, 0, 0, 0);
;     S.o1 = __builtin_amdgcn_mfma_f32_32x32x16_bf16(ATT_VF(3), ATT_PF(pa1), S.o1, 0, 0, 0);
;     S.o0 = __builtin_amdgcn_mfma_f32_32x32x16_bf16(ATT_VF(4), ATT_PF(pb0), S.o0, 0, 0, 0);
;     S.o1 = __builtin_amdgcn_mfma_f32_32x32x16_bf16(ATT_VF(6), ATT_PF(pb0), S.o1, 0, 0, 0);
;     S.o0 = __builtin_amdgcn_mfma_f32_32x32x16_bf16(ATT_VF(5), ATT_PF(pb1), S.o0, 0, 0, 0);
;     S.o1 = __builtin_amdgcn_mfma_f32_32x32x16_bf16(ATT_VF(7), ATT_PF(pb1), S.o1, 0, 0, 0);
; template <int MODE> ...
;     ...
;     for (int s = T0; s < T1; ++s) {
;         const int t = SU_T(s);
;         const bool more = (s + 2 < T1);
;         if (more) { glds16(kg + (size_t)SU_T(s + 2) * 4096, kdst + s2); glds16(vg + (size_t)SU_T(s + 2) * 4096, vdst + s2); }
;         LAS unsigned char* buf = ring + s0;
;         if (t >= t_lo && t < t_hi)
;             step64<MODE>(S, qf, t, qpos0, t == t_hi - 1, REV ? (t == t_hi - 1) : (t == t_lo), cq, cfar, tab, buf, (unsigned)(unsigned long)(buf + 8192) + vl, r32, hi);
;         if (more) asm volatile("s_waitcnt vmcnt(2) lgkmcnt(0)\n\ts_barrier" ::: "memory");
.Lr0_top:
	s_mov_b32 s50, s0
	s_add_i32 s0, s44, 2
	s_cmp_ge_u32 s0, s15
	s_cselect_b64 s[46:47], -1, 0
	s_and_b64 vcc, exec, s[46:47]
	s_cbranch_vccnz .Lr0_nodma
	s_add_i32 s1, s49, s24
	s_mov_b32 s2, m0
	s_mov_b32 m0, s1
	s_nop 0
	global_load_lds_dwordx4 v[124:125], off
	s_add_i32 s0, s49, s25
	s_mov_b32 m0, s0
	s_nop 0
	global_load_lds_dwordx4 v[122:123], off
	s_mov_b32 m0, s2
.Lr0_nodma:
	s_sub_i32 s34, s41, 8
	s_max_i32 s34, s34, 0
	s_cmp_le_i32 s44, s34
	s_cbranch_scc1 .Lr0_noY
	s_add_i32 s35, s41, 1
	s_cmp_gt_i32 s44, s35
	s_cbranch_scc1 .Lr0_noY
	s_waitcnt lgkmcnt(0)
	s_cmp_gt_i32 s44, s41
	s_cbranch_scc1 .Lr0a_pv
	s_add_i32 s35, s48, 63
	s_min_i32 s35, s35, 192
	s_lshl_b32 s35, s35, 2
	v_subrev_u32_e32 v15, s35, v238
	ds_read_b128 v[186:189], v15
	ds_read_b128 v[190:193], v15 offset:32
	ds_read_b128 v[194:197], v15 offset:64
	ds_read_b128 v[198:201], v15 offset:96
	ds_read_b128 v[202:205], v15 offset:128
	ds_read_b128 v[206:209], v15 offset:160
	ds_read_b128 v[210:213], v15 offset:192
	ds_read_b128 v[214:217], v15 offset:224
.Lr0a_pv:
	v_exp_f32_e32 v48, v48
	v_exp_f32_e32 v49, v49
	v_exp_f32_e32 v50, v50
	v_exp_f32_e32 v51, v51
	v_exp_f32_e32 v52, v52
	v_exp_f32_e32 v53, v53
	v_exp_f32_e32 v54, v54
	v_exp_f32_e32 v55, v55
	v_cvt_pk_bf16_f32 v218, v48, v49
	v_cvt_pk_bf16_f32 v219, v50, v51
	v_cvt_pk_bf16_f32 v220, v52, v53
	v_cvt_pk_bf16_f32 v221, v54, v55
	v_exp_f32_e32 v56, v56
	v_exp_f32_e32 v57, v57
	v_mfma_f32_32x32x16_bf16 v[32:47], v[112:115], v[218:221], v[32:47]
	v_exp_f32_e32 v58, v58
	v_exp_f32_e32 v59, v59
	v_exp_f32_e32 v60, v60
	v_exp_f32_e32 v61, v61
	v_exp_f32_e32 v62, v62
	v_exp_f32_e32 v63, v63
	v_mfma_f32_32x32x16_bf16 v[16:31], v[108:111], v[218:221], v[16:31]
	v_cvt_pk_bf16_f32 v222, v56, v57
	v_cvt_pk_bf16_f32 v223, v58, v59
	v_cvt_pk_bf16_f32 v224, v60, v61
	v_cvt_pk_bf16_f32 v225, v62, v63
	v_add_f32_e32 v0, v48, v50
	v_add_f32_e32 v0, v0, v52
	v_add_f32_e32 v14, v49, v51
	v_add_f32_e32 v14, v14, v53
	v_mfma_f32_32x32x16_bf16 v[32:47], v[104:107], v[222:225], v[32:47]
	v_exp_f32_e32 v64, v64
	v_exp_f32_e32 v65, v65
	v_exp_f32_e32 v66, v66
	v_exp_f32_e32 v67, v67
	v_exp_f32_e32 v68, v68
	v_exp_f32_e32 v69, v69
	v_exp_f32_e32 v70, v70
	v_exp_f32_e32 v71, v71
	v_mfma_f32_32x32x16_bf16 v[16:31], v[100:103], v[222:225], v[16:31]
	v_cvt_pk_bf16_f32 v226, v64, v65
	v_cvt_pk_bf16_f32 v227, v66, v67
	v_cvt_pk_bf16_f32 v228, v68, v69
	v_cvt_pk_bf16_f32 v229, v70, v71
	v_add_f32_e32 v0, v0, v54
	v_add_f32_e32 v0, v0, v56
	v_add_f32_e32 v14, v14, v55
	v_add_f32_e32 v14, v14, v57
	v_mfma_f32_32x32x16_bf16 v[32:47], v[96:99], v[226:229], v[32:47]
	v_exp_f32_e32 v72, v72
	v_exp_f32_e32 v73, v73
	v_exp_f32_e32 v74, v74
	v_exp_f32_e32 v75, v75
	v_exp_f32_e32 v76, v76
	v_exp_f32_e32 v77, v77
	v_exp_f32_e32 v78, v78
	v_exp_f32_e32 v79, v79
	v_mfma_f32_32x32x16_bf16 v[16:31], v[10:13], v[226:229], v[16:31]
	v_cvt_pk_bf16_f32 v230, v72, v73
	v_cvt_pk_bf16_f32 v231, v74, v75
	v_cvt_pk_bf16_f32 v232, v76, v77
	v_cvt_pk_bf16_f32 v233, v78, v79
	v_add_f32_e32 v0, v0, v58
	v_add_f32_e32 v0, v0, v60
	v_add_f32_e32 v0, v0, v62
	v_add_f32_e32 v14, v14, v59
	v_add_f32_e32 v14, v14, v61
	v_add_f32_e32 v14, v14, v63
	v_mfma_f32_32x32x16_bf16 v[32:47], v[6:9], v[230:233], v[32:47]
	v_add_f32_e32 v15, v64, v66
	v_add_f32_e32 v15, v15, v68
	v_add_f32_e32 v15, v15, v70
	v_add_f32_e32 v15, v15, v72
	v_add_f32_e32 v234, v65, v67
	v_add_f32_e32 v234, v234, v69
	v_add_f32_e32 v234, v234, v71
	v_add_f32_e32 v234, v234, v73
	v_mfma_f32_32x32x16_bf16 v[16:31], v[2:5], v[230:233], v[16:31]
	v_add_f32_e32 v15, v15, v74
	v_add_f32_e32 v15, v15, v76
	v_add_f32_e32 v15, v15, v78
	v_add_f32_e32 v234, v234, v75
	v_add_f32_e32 v234, v234, v77
	v_add_f32_e32 v234, v234, v79
	v_add_f32_e32 v0, v0, v14
	v_add_f32_e32 v15, v15, v234
	v_add_f32_e32 v0, v0, v15
	v_add_f32_e32 v150, v150, v0
	s_cmp_gt_i32 s44, s41
	s_cbranch_scc1 .Lr0a_end
	s_waitcnt lgkmcnt(0)
	v_sub_f32_e32 v48, v186, v157
	v_sub_f32_e32 v49, v187, v157
	v_sub_f32_e32 v50, v188, v157
	v_sub_f32_e32 v51, v189, v157
	v_sub_f32_e32 v52, v190, v157
	v_sub_f32_e32 v53, v191, v157
	v_sub_f32_e32 v54, v192, v157
	v_sub_f32_e32 v55, v193, v157
	v_sub_f32_e32 v56, v194, v157
	v_sub_f32_e32 v57, v195, v157
	v_sub_f32_e32 v58, v196, v157
	v_sub_f32_e32 v59, v197, v157
	v_sub_f32_e32 v60, v198, v157
	v_sub_f32_e32 v61, v199, v157
	v_sub_f32_e32 v62, v200, v157
	v_sub_f32_e32 v63, v201, v157
	v_sub_f32_e32 v64, v202, v157
	v_sub_f32_e32 v65, v203, v157
	v_sub_f32_e32 v66, v204, v157
	v_sub_f32_e32 v67, v205, v157
	v_sub_f32_e32 v68, v206, v157
	v_sub_f32_e32 v69, v207, v157
	v_sub_f32_e32 v70, v208, v157
	v_sub_f32_e32 v71, v209, v157
	v_sub_f32_e32 v72, v210, v157
	v_sub_f32_e32 v73, v211, v157
	v_sub_f32_e32 v74, v212, v157
	v_sub_f32_e32 v75, v213, v157
	v_sub_f32_e32 v76, v214, v157
	v_sub_f32_e32 v77, v215, v157
	v_sub_f32_e32 v78, v216, v157
	v_sub_f32_e32 v79, v217, v157
; #define LAS __attribute__((address_space(3)))
; __device__ __forceinline__ int crow(int r, int hi) { return (r & 3) + 8 * (r >> 2) + 4 * hi; }
; template <int MODE>
; __device__ __forceinline__ void step64(St& S, const bf16x8 (&qf)[4], int t, int qpos0, bool diag, bool first, float cq, float cfar, const LAS float* tab,
;                                        const LAS unsigned char* buf, unsigned vaddr, int r32, int hi) {
;     bf16x8 ka[4], kc[4];
; #pragma unroll
;     for (int d0 = 0; d0 < 4; ++d0) { const int o = r32 * 128 + (((d0 * 2 + hi) ^ ((r32 >> 1) & 7)) << 4); ka[d0] = *(const LAS bf16x8*)(buf + o); kc[d0] = *(const LAS bf16x8*)(buf + 4096 + o); }
;     f32x16 sa, sb;
;     if (MODE == 1) {
;         const float nm = cq - S.m;
; #pragma unroll
;         for (int g = 0; g < 4; ++g) { const f32x4 c0 = *(const LAS f32x4*)(tab + t * 64 + 8 * g + 4 * hi), c1 = *(const LAS f32x4*)(tab + t * 64 + 32 + 8 * g + 4 * hi);
; #pragma unroll
;             for (int e = 0; e < 4; ++e) { sa[4 * g + e] = nm - c0[e]; sb[4 * g + e] = nm - c1[e]; } }
;     } else {
;         if (qpos0 - (t * 64 + 31) >= 128) {
;             const float c = cfar - S.m;
; #pragma unroll
;             for (int r = 0; r < 16; ++r) sa[r] = c;
;         } else {
;             const int dd = qpos0 + r32 - t * 64 + 128;
; #pragma unroll
;             for (int r = 0; r < 16; ++r) { int idx = dd - crow(r, hi); idx = idx < 0 ? 0 : (idx > 256 ? 256 : idx); sa[r] = tab[idx] - S.m; }
.Lr0a_end:
.Lr0_noY:
	s_cmp_gt_i32 s44, s41
	s_cbranch_scc1 .Lr0_norescale
	s_sub_i32 s34, s41, 8
	s_max_i32 s34, s34, 0
	s_cmp_lt_i32 s44, s34
	s_cbranch_scc1 .Lr0_norescale
	s_add_i32 s2, s50, 0
	s_add_i32 s5, s2, 0x6800
	s_sub_i32 s34, s41, 8
	s_max_i32 s34, s34, 0
	v_add_u32_e32 v0, s2, v152
	v_add_u32_e32 v14, s2, v153
	v_add_u32_e32 v15, s2, v154
	v_add_u32_e32 v234, s2, v155
	ds_read_b128 v[186:189], v0 offset:18432
	ds_read_b128 v[194:197], v14 offset:18432
	ds_read_b128 v[202:205], v15 offset:18432
	ds_read_b128 v[210:213], v234 offset:18432
	ds_read_b128 v[190:193], v0 offset:22528
	ds_read_b128 v[198:201], v14 offset:22528
	ds_read_b128 v[206:209], v15 offset:22528
	ds_read_b128 v[214:217], v234 offset:22528
	v_add_u32_e32 v0, s5, v151
	s_cmp_eq_u32 s44, s34
	s_cbranch_scc0 .Lr0_have_init
	s_add_i32 s35, s48, 63
	s_min_i32 s35, s35, 192
	s_lshl_b32 s35, s35, 2
	v_subrev_u32_e32 v15, s35, v238
	ds_read_b128 v[112:115], v15
	ds_read_b128 v[104:107], v15 offset:32
	ds_read_b128 v[108:111], v15 offset:64
	ds_read_b128 v[100:103], v15 offset:96
	ds_read_b128 v[96:99], v15 offset:128
	ds_read_b128 v[6:9], v15 offset:160
	ds_read_b128 v[10:13], v15 offset:192
	ds_read_b128 v[2:5], v15 offset:224
	s_waitcnt lgkmcnt(0)
	v_sub_f32_e32 v48, v112, v157
	v_sub_f32_e32 v49, v113, v157
	v_sub_f32_e32 v50, v114, v157
	v_sub_f32_e32 v51, v115, v157
	v_sub_f32_e32 v52, v104, v157
	v_sub_f32_e32 v53, v105, v157
	v_sub_f32_e32 v54, v106, v157
	v_sub_f32_e32 v55, v107, v157
	v_sub_f32_e32 v56, v108, v157
	v_sub_f32_e32 v57, v109, v157
	v_sub_f32_e32 v58, v110, v157
	v_sub_f32_e32 v59, v111, v157
	v_sub_f32_e32 v60, v100, v157
	v_sub_f32_e32 v61, v101, v157
	v_sub_f32_e32 v62, v102, v157
	v_sub_f32_e32 v63, v103, v157
	v_sub_f32_e32 v64, v96, v157
	v_sub_f32_e32 v65, v97, v157
	v_sub_f32_e32 v66, v98, v157
	v_sub_f32_e32 v67, v99, v157
	v_sub_f32_e32 v68, v6, v157
	v_sub_f32_e32 v69, v7, v157
	v_sub_f32_e32 v70, v8, v157
	v_sub_f32_e32 v71, v9, v157
	v_sub_f32_e32 v72, v10, v157
	v_sub_f32_e32 v73, v11, v157
	v_sub_f32_e32 v74, v12, v157
	v_sub_f32_e32 v75, v13, v157
	v_sub_f32_e32 v76, v2, v157
	v_sub_f32_e32 v77, v3, v157
	v_sub_f32_e32 v78, v4, v157
	v_sub_f32_e32 v79, v5, v157
	s_nop 1

; template <int MODE> ...
;     ...
;         if (more) asm volatile("s_waitcnt vmcnt(2) lgkmcnt(0)\n\ts_barrier" ::: "memory");
;         else      asm volatile("s_waitcnt vmcnt(0) lgkmcnt(0)\n\ts_barrier" ::: "memory");
;         const int sn = s0; s0 = s1; s1 = s2; s2 = sn;
;     }
.Lr0_norescale:
	s_and_b64 vcc, exec, s[46:47]
	s_cbranch_vccnz .Lr0_bar0
	s_waitcnt vmcnt(2) lgkmcnt(0)
	s_barrier
	s_branch .Lr0_ctl
.Lr0_bar0:
	s_waitcnt vmcnt(0) lgkmcnt(0)
	s_barrier
.Lr0_ctl:
	s_add_i32 s44, s44, 1
	s_sub_i32 s48, s48, 64
	v_lshl_add_u64 v[122:123], v[122:123], 0, s[66:67]
	s_cmp_ge_u32 s44, s15
	v_lshl_add_u64 v[124:125], v[124:125], 0, s[66:67]
	s_cbranch_scc1 .Lr0_epi
	s_mov_b32 s0, s45
	s_mov_b32 s45, s49
	s_mov_b32 s49, s50
	s_branch .Lr0_top
.Lr0_epi:
	s_add_i32 s35, s41, 1
	s_cmp_gt_i32 s44, s35
	s_cbranch_scc1 .Lr0_done
	s_waitcnt lgkmcnt(0)
	s_cmp_gt_i32 s44, s41
	s_cbranch_scc1 .Lr0b_pv
	s_add_i32 s35, s48, 63
	s_min_i32 s35, s35, 192
	s_lshl_b32 s35, s35, 2
	v_subrev_u32_e32 v15, s35, v238
	ds_read_b128 v[186:189], v15
	ds_read_b128 v[190:193], v15 offset:32
	ds_read_b128 v[194:197], v15 offset:64
	ds_read_b128 v[198:201], v15 offset:96
	ds_read_b128 v[202:205], v15 offset:128
	ds_read_b128 v[206:209], v15 offset:160
	ds_read_b128 v[210:213], v15 offset:192
	ds_read_b128 v[214:217], v15 offset:224

; template <int MODE> ...
;     ...
;         const int sn = s0; s0 = s1; s1 = s2; s2 = sn;
;     }
;     ...
;     finish(S, Yrow, Grow, ring + 49152 + w * 8704, lane);
.Lr0b_end:
	s_nop 7
	s_nop 4
.Lr0_done:
	s_branch .LBB0_656
.LBB0_631:
	s_and_b64 vcc, exec, s[0:1]
	s_cbranch_vccz .LBB0_633
	v_mov_b32_e32 v14, v1
	v_mov_b32_e32 v15, v1
	v_mov_b32_e32 v0, v1
	v_mov_b32_e32 v2, v1
	v_mov_b32_e32 v3, v1
	v_mov_b32_e32 v4, v1
	v_mov_b32_e32 v5, v1
	v_mov_b32_e32 v6, v1
	v_mov_b32_e32 v7, v1
	v_mov_b32_e32 v8, v1
	v_mov_b32_e32 v9, v1
	v_mov_b32_e32 v10, v1
	v_mov_b32_e32 v11, v1
	v_mov_b32_e32 v12, v1
	v_mov_b32_e32 v13, v1
	v_mov_b64_e32 v[46:47], v[14:15]
	v_mov_b64_e32 v[30:31], v[14:15]
	v_mov_b32_e32 v150, 0
	v_mov_b32_e32 v146, v147
	v_mov_b64_e32 v[44:45], v[12:13]
	v_mov_b64_e32 v[42:43], v[10:11]
	v_mov_b64_e32 v[40:41], v[8:9]
	v_mov_b64_e32 v[38:39], v[6:7]
	v_mov_b64_e32 v[36:37], v[4:5]
	v_mov_b64_e32 v[34:35], v[2:3]
	v_mov_b64_e32 v[32:33], v[0:1]
	v_mov_b64_e32 v[28:29], v[12:13]
	v_mov_b64_e32 v[26:27], v[10:11]
	v_mov_b64_e32 v[24:25], v[8:9]
	v_mov_b64_e32 v[22:23], v[6:7]
	v_mov_b64_e32 v[20:21], v[4:5]
	v_mov_b64_e32 v[18:19], v[2:3]
	v_mov_b64_e32 v[16:17], v[0:1]

; __device__ __forceinline__ unsigned v_lane_off(int lane) { return (unsigned)((4 * (lane >> 5) + ((lane & 15) >> 2)) * 64 + ((lane >> 4) & 1) * 32 + (lane & 3) * 8); }
; template <int MODE> ...
;     ...
;     bf16x8 qf[4];
; #pragma unroll
;     for (int d0 = 0; d0 < 4; ++d0) qf[d0] = *(const bf16x8*)(Qrow + r32 * 64 + d0 * 16 + hi * 8);
;     const int kkey = 8 * w + (lane >> 3), kch = (lane & 7) ^ ((kkey >> 1) & 7);
;     const int vkey = 8 * w + ((lane >> 2) & 7), vch = 4 * ((lane >> 5) & 1) + (lane & 3);
;     const bf16_t* kg = Kb + kkey * 64 + kch * 8;
;     const bf16_t* vg = Vb + vkey * 64 + vch * 8;
;     const unsigned ring0 = (unsigned)(unsigned long)ring;
;     const unsigned kdst = (unsigned)__builtin_amdgcn_readfirstlane(ring0 + w * 1024), vdst = kdst + 8192;
;     const float cq = (MODE == 1) ? tab[qpos0 + r32] : 0.f;
;     const float cfar = (MODE == 0) ? tab[256] : 0.f;
;     const unsigned vl = v_lane_off(lane);
;     St S; st_init(S);
;     asm volatile("" :: "v"(qf[0]), "v"(qf[1]), "v"(qf[2]), "v"(qf[3]));
;     constexpr bool REV = (MODE == 1);
;     ...
;     int s0 = 0, s1 = 16384, s2 = 32768;
;     glds16(kg + (size_t)SU_T(T0) * 4096, kdst + s0); glds16(vg + (size_t)SU_T(T0) * 4096, vdst + s0);
;     if (T0 + 1 < T1) { glds16(kg + (size_t)SU_T(T0 + 1) * 4096, kdst + s1); glds16(vg + (size_t)SU_T(T0 + 1) * 4096, vdst + s1);
;                        asm volatile("s_waitcnt vmcnt(2) lgkmcnt(0)\n\ts_barrier" ::: "memory"); }
;     else             { asm volatile("s_waitcnt vmcnt(0) lgkmcnt(0)\n\ts_barrier" ::: "memory"); }
.LBB0_634:
	s_and_b64 vcc, exec, s[0:1]
	s_cbranch_vccz .LBB0_597
	v_mov_b32_e32 v123, v120
	v_mov_b32_e32 v5, v1
	v_and_b32_e32 v124, 31, v123
	v_bfe_u32 v6, v123, 5, 1
	v_lshlrev_b32_e32 v0, 7, v124
	v_lshl_add_u64 v[2:3], s[42:43], 0, v[0:1]
	v_lshlrev_b32_e32 v4, 4, v6
	v_lshl_add_u64 v[2:3], v[2:3], 0, v[4:5]
	global_load_dwordx4 v[80:83], v[2:3], off
	global_load_dwordx4 v[84:87], v[2:3], off offset:32
	global_load_dwordx4 v[88:91], v[2:3], off offset:64
	global_load_dwordx4 v[92:95], v[2:3], off offset:96
	s_lshl_b32 s4, s21, 14
	s_lshl_b32 s1, s12, 2
	s_mov_b32 s3, s13
	s_or_b32 s2, s4, 0x3000
	v_readfirstlane_b32 s10, v123
	s_sub_i32 s15, 0, s6
	s_add_i32 s1, s1, 0
	v_lshrrev_b32_e32 v8, 3, v123
	v_bfe_u32 v9, v123, 2, 2
	v_lshlrev_b32_e32 v10, 1, v123
	s_lshl_b64 s[6:7], s[2:3], 1
	v_lshrrev_b32_e32 v125, 1, v123
	s_ashr_i32 s2, s10, 6
	v_bfe_u32 v122, v123, 3, 3
	v_lshlrev_b32_e32 v5, 3, v123
	v_lshl_add_u32 v12, v124, 2, s1
	v_and_or_b32 v8, v8, 4, v9
	v_and_b32_e32 v9, 32, v10
	v_bitop3_b32 v10, v6, v125, 7 bitop3:0x78
	s_lshl_b32 s1, s2, 3
	v_lshrrev_b32_e32 v2, 2, v123
	v_bfe_u32 v11, v123, 1, 3
	v_and_b32_e32 v5, 24, v5
	v_lshlrev_b32_e32 v8, 6, v8
	v_lshl_or_b32 v143, v10, 4, v0
	v_or_b32_e32 v10, s1, v122
	v_bitop3_b32 v13, v6, v11, 2 bitop3:0x36
	v_bitop3_b32 v14, v6, v11, 4 bitop3:0x36
	v_bitop3_b32 v11, v6, v11, 6 bitop3:0x36
	v_lshlrev_b32_e32 v16, 2, v6
	v_and_or_b32 v6, v123, 32, v5
	v_and_or_b32 v2, v2, 7, s1
	v_or3_b32 v147, v5, v9, v8
	v_lshrrev_b32_e32 v5, 1, v10
	v_lshlrev_b32_e32 v8, 6, v10
	v_lshlrev_b32_e32 v10, 6, v2
	v_xor_b32_e32 v2, v5, v123
	v_lshl_or_b32 v146, v11, 4, v0
	v_ashrrev_i32_e32 v9, 31, v8
	v_ashrrev_i32_e32 v11, 31, v10
	v_lshlrev_b32_e32 v2, 4, v2
	v_mov_b32_e32 v3, v1
	v_mov_b32_e32 v7, v1
	s_mov_b32 s5, s13
	s_bitset1_b32 s4, 13
	s_lshl_b32 s3, s2, 10
	v_lshlrev_b32_e32 v6, 1, v6
	v_lshl_add_u64 v[8:9], v[8:9], 1, s[36:37]
	v_lshl_add_u64 v[10:11], v[10:11], 1, s[38:39]
	v_and_b32_e32 v2, 0x70, v2
	s_lshl_b64 s[4:5], s[4:5], 1
	s_add_i32 s1, s3, 0
	v_lshl_add_u64 v[6:7], v[10:11], 0, v[6:7]
	v_lshl_add_u64 v[2:3], v[8:9], 0, v[2:3]
	ds_read_b32 v142, v12
	v_lshl_or_b32 v144, v13, 4, v0
	v_lshl_or_b32 v145, v14, 4, v0
	s_add_i32 s20, s1, 0x4800
	v_lshl_add_u64 v[10:11], v[6:7], 0, s[4:5]
	v_lshl_add_u64 v[12:13], v[2:3], 0, s[6:7]
	v_lshl_add_u64 v[14:15], v[2:3], 0, s[4:5]
	s_add_i32 s3, s1, 0x6800
	v_lshl_add_u64 v[8:9], v[6:7], 0, s[6:7]
	s_lshr_b32 s28, s40, 1
	s_add_i32 s10, s1, 0x8800
	s_add_i32 s1, s1, 0xa800
	v_or_b32_e32 v0, 32, v16
	v_or_b32_e32 v17, 33, v16
	v_or_b32_e32 v5, 2, v16
	v_or_b32_e32 v18, 42, v16
	v_or_b32_e32 v19, 11, v16
	v_or_b32_e32 v20, 43, v16
	v_or_b32_e32 v21, 16, v16
	v_or_b32_e32 v22, 48, v16
	v_or_b32_e32 v23, 17, v16
	s_mov_b32 s4, m0
	s_mov_b32 m0, s20
	s_nop 0
	global_load_lds_dwordx4 v[12:13], off
	s_mov_b32 m0, s4
	v_or_b32_e32 v12, 40, v16
	s_mov_b32 s4, m0
	s_mov_b32 m0, s3
	s_nop 0
	global_load_lds_dwordx4 v[8:9], off
	s_mov_b32 m0, s4
	v_or_b32_e32 v8, 34, v16
	s_mov_b32 s4, m0
	s_mov_b32 m0, s10
	s_nop 0
	global_load_lds_dwordx4 v[14:15], off
	s_mov_b32 m0, s4
	v_or_b32_e32 v14, 41, v16
	s_mov_b32 s4, m0
	s_mov_b32 m0, s1
	s_nop 0
	global_load_lds_dwordx4 v[10:11], off
	s_mov_b32 m0, s4
	s_lshl_b32 s1, s28, 6
	s_sub_i32 s1, s12, s1
	v_or_b32_e32 v15, 10, v16
	v_or_b32_e32 v37, s1, v124
	s_waitcnt vmcnt(2) lgkmcnt(0)
	s_barrier
	v_or_b32_e32 v9, 3, v16
	v_or_b32_e32 v10, 35, v16
	v_or_b32_e32 v11, 8, v16
	v_or_b32_e32 v13, 9, v16
	v_or_b32_e32 v24, 49, v16
	v_or_b32_e32 v25, 18, v16
	v_or_b32_e32 v26, 50, v16
	v_or_b32_e32 v27, 19, v16
	v_or_b32_e32 v28, 51, v16
	v_or_b32_e32 v29, 24, v16
	v_or_b32_e32 v30, 56, v16
	v_or_b32_e32 v31, 25, v16
	v_or_b32_e32 v32, 57, v16
	v_or_b32_e32 v33, 26, v16
	v_or_b32_e32 v34, 58, v16
	v_or_b32_e32 v35, 27, v16
	v_or_b32_e32 v36, 59, v16
	v_cmp_gt_i32_e64 s[56:57], v14, v37
	v_cmp_gt_i32_e64 s[58:59], v15, v37
	v_mov_b32_e32 v14, v1
	v_mov_b32_e32 v15, v1
	s_mov_b32 s23, s86
	s_lshl_b32 s33, s21, 2
	v_cmp_gt_i32_e64 s[34:35], v16, v37
	v_cmp_gt_i32_e64 s[36:37], v0, v37
	v_cmp_lt_i32_e64 s[38:39], v16, v37
	v_cmp_gt_i32_e64 s[40:41], v17, v37
	v_cmp_gt_i32_e64 s[42:43], v5, v37
	v_cmp_gt_i32_e64 s[44:45], v8, v37
	v_cmp_gt_i32_e64 s[46:47], v9, v37
	v_cmp_gt_i32_e64 s[48:49], v10, v37
	v_cmp_gt_i32_e64 s[50:51], v11, v37
	v_cmp_gt_i32_e64 s[52:53], v12, v37
	v_cmp_gt_i32_e64 s[54:55], v13, v37
	v_cmp_gt_i32_e64 s[60:61], v18, v37
	v_cmp_gt_i32_e64 s[62:63], v19, v37
	v_cmp_gt_i32_e64 s[64:65], v20, v37
	v_cmp_gt_i32_e64 s[66:67], v21, v37
	v_cmp_gt_i32_e64 s[68:69], v22, v37
	v_cmp_gt_i32_e64 s[70:71], v23, v37
	v_cmp_gt_i32_e64 s[72:73], v24, v37
	v_cmp_gt_i32_e64 s[74:75], v25, v37
	v_cmp_gt_i32_e64 s[76:77], v26, v37
	v_cmp_gt_i32_e64 s[78:79], v27, v37
	v_cmp_gt_i32_e64 s[80:81], v28, v37
	v_cmp_gt_i32_e64 s[82:83], v29, v37
	v_cmp_gt_i32_e64 s[84:85], v30, v37
	v_cmp_gt_i32_e64 s[86:87], v31, v37
	v_cmp_gt_i32_e64 s[88:89], v32, v37
	v_cmp_gt_i32_e64 s[90:91], v33, v37
	v_cmp_gt_i32_e64 s[92:93], v34, v37
	v_cmp_gt_i32_e64 s[94:95], v35, v37
	v_cmp_gt_i32_e64 s[96:97], v36, v37
	v_lshl_add_u64 v[116:117], v[6:7], 0, s[30:31]
	v_lshl_add_u64 v[118:119], v[2:3], 0, s[30:31]
	v_add_u32_e32 v148, s14, v4
	v_mov_b32_e32 v0, v1
	v_mov_b32_e32 v2, v1
	v_mov_b32_e32 v3, v1
	v_mov_b32_e32 v4, v1
	v_mov_b32_e32 v5, v1
	v_mov_b32_e32 v6, v1
	v_mov_b32_e32 v7, v1
	v_mov_b32_e32 v8, v1
	v_mov_b32_e32 v9, v1
	v_mov_b32_e32 v10, v1
	v_mov_b32_e32 v11, v1
	v_mov_b32_e32 v12, v1
	v_mov_b32_e32 v13, v1
	v_mov_b64_e32 v[30:31], v[14:15]
	v_mov_b64_e32 v[46:47], v[14:15]
	s_mov_b32 s0, 0
	s_mov_b32 s19, 2
	s_add_i32 s33, s33, 4
	v_mov_b32_e32 v150, 0
	s_mov_b32 s12, 0x8000
	s_movk_i32 s10, 0x4000
	s_mov_b32 s1, s18
	v_mov_b32_e32 v149, 0
	v_mov_b64_e32 v[28:29], v[12:13]
	v_mov_b64_e32 v[26:27], v[10:11]
	v_mov_b64_e32 v[24:25], v[8:9]
	v_mov_b64_e32 v[22:23], v[6:7]
	v_mov_b64_e32 v[20:21], v[4:5]
	v_mov_b64_e32 v[18:19], v[2:3]
	v_mov_b64_e32 v[16:17], v[0:1]
	v_mov_b64_e32 v[44:45], v[12:13]
	v_mov_b64_e32 v[42:43], v[10:11]
	v_mov_b64_e32 v[40:41], v[8:9]
	v_mov_b64_e32 v[38:39], v[6:7]
	v_mov_b64_e32 v[36:37], v[4:5]
	v_mov_b64_e32 v[34:35], v[2:3]
	v_mov_b64_e32 v[32:33], v[0:1]
	s_cmp_ge_u32 s23, 4
	s_cbranch_scc1 .Lr1_top

; #define LAS __attribute__((address_space(3)))
; template <int MODE>
; __device__ __forceinline__ void step64(St& S, const bf16x8 (&qf)[4], int t, int qpos0, bool diag, bool first, float cq, float cfar, const LAS float* tab,
;                                        const LAS unsigned char* buf, unsigned vaddr, int r32, int hi) {
;     ...
;     for (int d0 = 0; d0 < 4; ++d0) { const int o = r32 * 128 + (((d0 * 2 + hi) ^ ((r32 >> 1) & 7)) << 4); ka[d0] = *(const LAS bf16x8*)(buf + o); kc[d0] = *(const LAS bf16x8*)(buf + 4096 + o); }
;     f32x16 sa, sb;
;     if (MODE == 1) {
;         const float nm = cq - S.m;
; #pragma unroll
;     ...
;     for (int r = 0; r < 16; ++r) { sa[r] = __builtin_amdgcn_exp2f(sa[r]); sb[r] = __builtin_amdgcn_exp2f(sb[r]); }
;     asm volatile("s_waitcnt lgkmcnt(0)" ::: "memory");
;     __builtin_amdgcn_sched_barrier(0);
;     u32x4 pa0, pa1, pb0, pb1;
;     pa0.x = pk2(sa[0], sa[1]); pa0.y = pk2(sa[2], sa[3]); pa0.z = pk2(sa[4], sa[5]); pa0.w = pk2(sa[6], sa[7]);
;     pa1.x = pk2(sa[8], sa[9]); pa1.y = pk2(sa[10], sa[11]); pa1.z = pk2(sa[12], sa[13]); pa1.w = pk2(sa[14], sa[15]);
;     pb0.x = pk2(sb[0], sb[1]); pb0.y = pk2(sb[2], sb[3]); pb0.z = pk2(sb[4], sb[5]); pb0.w = pk2(sb[6], sb[7]);
;     pb1.x = pk2(sb[8], sb[9]); pb1.y = pk2(sb[10], sb[11]); pb1.z = pk2(sb[12], sb[13]); pb1.w = pk2(sb[14], sb[15]);
;     ...
;     S.o0 = __builtin_amdgcn_mfma_f32_32x32x16_bf16(ATT_VF(0), ATT_PF(pa0), S.o0, 0, 0, 0);
;     S.o1 = __builtin_amdgcn_mfma_f32_32x32x16_bf16(ATT_VF(2), ATT_PF(pa0), S.o1, 0, 0, 0);
;     S.o0 = __builtin_amdgcn_mfma_f32_32x32x16_bf16(ATT_VF(1), ATT_PF(pa1), S.o0, 0, 0, 0);
;     S.o1 = __builtin_amdgcn_mfma_f32_32x32x16_bf16(ATT_VF(3), ATT_PF(pa1), S.o1, 0, 0, 0);
;     S.o0 = __builtin_amdgcn_mfma_f32_32x32x16_bf16(ATT_VF(4), ATT_PF(pb0), S.o0, 0, 0, 0);
;     S.o1 = __builtin_amdgcn_mfma_f32_32x32x16_bf16(ATT_VF(6), ATT_PF(pb0), S.o1, 0, 0, 0);
;     S.o0 = __builtin_amdgcn_mfma_f32_32x32x16_bf16(ATT_VF(5), ATT_PF(pb1), S.o0, 0, 0, 0);
;     S.o1 = __builtin_amdgcn_mfma_f32_32x32x16_bf16(ATT_VF(7), ATT_PF(pb1), S.o1, 0, 0, 0);
;     ...
;     float l0 = 0.f, l1 = 0.f, l2 = 0.f, l3 = 0.f;
; #pragma unroll
;     for (int r = 0; r < 16; r += 2) { l0 += sa[r]; l1 += sa[r + 1]; l2 += sb[r]; l3 += sb[r + 1]; }
;     S.l += (l0 + l1) + (l2 + l3);
.Lr1_top:
	s_cmp_ge_u32 s19, s33
	s_cselect_b64 s[24:25], -1, 0
	s_mov_b32 s11, s0
	s_and_b64 vcc, exec, s[24:25]
	s_cbranch_vccnz .Lr1_nodma
	s_add_i32 s4, s12, s20
	s_mov_b32 s5, m0
	s_mov_b32 m0, s4
	s_nop 0
	global_load_lds_dwordx4 v[118:119], off
	s_add_i32 s0, s12, s3
	s_mov_b32 m0, s0
	s_nop 0
	global_load_lds_dwordx4 v[116:117], off
	s_mov_b32 m0, s5
.Lr1_nodma:
	s_add_i32 s22, s1, -1
	s_cmp_lt_i32 s22, s28
	s_cbranch_scc0 .Lr1_noY
	s_waitcnt lgkmcnt(0)
	ds_read_b128 v[186:189], v148
	ds_read_b128 v[190:193], v148 offset:32
	ds_read_b128 v[194:197], v148 offset:64
	ds_read_b128 v[198:201], v148 offset:96
	ds_read_b128 v[202:205], v148 offset:128
	ds_read_b128 v[206:209], v148 offset:160
	ds_read_b128 v[210:213], v148 offset:192
	ds_read_b128 v[214:217], v148 offset:224
	v_exp_f32_e32 v48, v48
	v_exp_f32_e32 v49, v49
	v_exp_f32_e32 v50, v50
	v_exp_f32_e32 v51, v51
	v_exp_f32_e32 v52, v52
	v_exp_f32_e32 v53, v53
	v_exp_f32_e32 v54, v54
	v_exp_f32_e32 v55, v55
	v_cvt_pk_bf16_f32 v152, v48, v49
	v_cvt_pk_bf16_f32 v153, v50, v51
	v_cvt_pk_bf16_f32 v154, v52, v53
	v_cvt_pk_bf16_f32 v155, v54, v55
	v_exp_f32_e32 v56, v56
	v_exp_f32_e32 v57, v57
	v_mfma_f32_32x32x16_bf16 v[32:47], v[112:115], v[152:155], v[32:47]
	v_exp_f32_e32 v58, v58
	v_exp_f32_e32 v59, v59
	v_exp_f32_e32 v60, v60
	v_exp_f32_e32 v61, v61
	v_exp_f32_e32 v62, v62
	v_exp_f32_e32 v63, v63
	v_mfma_f32_32x32x16_bf16 v[16:31], v[108:111], v[152:155], v[16:31]
	v_cvt_pk_bf16_f32 v156, v56, v57
	v_cvt_pk_bf16_f32 v157, v58, v59
	v_cvt_pk_bf16_f32 v158, v60, v61
	v_cvt_pk_bf16_f32 v159, v62, v63
	v_add_f32_e32 v0, v48, v50
	v_add_f32_e32 v0, v0, v52
	v_add_f32_e32 v14, v49, v51
	v_add_f32_e32 v14, v14, v53
	v_mfma_f32_32x32x16_bf16 v[32:47], v[104:107], v[156:159], v[32:47]
	v_exp_f32_e32 v64, v64
	v_exp_f32_e32 v65, v65
	v_exp_f32_e32 v66, v66
	v_exp_f32_e32 v67, v67
	v_exp_f32_e32 v68, v68
	v_exp_f32_e32 v69, v69
	v_exp_f32_e32 v70, v70
	v_exp_f32_e32 v71, v71
	v_mfma_f32_32x32x16_bf16 v[16:31], v[100:103], v[156:159], v[16:31]
	v_cvt_pk_bf16_f32 v160, v64, v65
	v_cvt_pk_bf16_f32 v161, v66, v67
	v_cvt_pk_bf16_f32 v162, v68, v69
	v_cvt_pk_bf16_f32 v163, v70, v71
	v_add_f32_e32 v0, v0, v54
	v_add_f32_e32 v0, v0, v56
	v_add_f32_e32 v14, v14, v55
	v_add_f32_e32 v14, v14, v57
	v_mfma_f32_32x32x16_bf16 v[32:47], v[96:99], v[160:163], v[32:47]
	v_exp_f32_e32 v72, v72
	v_exp_f32_e32 v73, v73
	v_exp_f32_e32 v74, v74
	v_exp_f32_e32 v75, v75
	v_exp_f32_e32 v76, v76
	v_exp_f32_e32 v77, v77
	v_exp_f32_e32 v78, v78
	v_exp_f32_e32 v79, v79
	v_mfma_f32_32x32x16_bf16 v[16:31], v[10:13], v[160:163], v[16:31]
	v_cvt_pk_bf16_f32 v234, v72, v73
	v_cvt_pk_bf16_f32 v235, v74, v75
	v_cvt_pk_bf16_f32 v236, v76, v77
	v_cvt_pk_bf16_f32 v237, v78, v79
	v_add_f32_e32 v0, v0, v58
	v_add_f32_e32 v0, v0, v60
	v_add_f32_e32 v0, v0, v62
	v_add_f32_e32 v14, v14, v59
	v_add_f32_e32 v14, v14, v61
	v_add_f32_e32 v14, v14, v63
	v_mfma_f32_32x32x16_bf16 v[32:47], v[6:9], v[234:237], v[32:47]
	v_add_f32_e32 v15, v64, v66
	v_add_f32_e32 v15, v15, v68
	v_add_f32_e32 v15, v15, v70
	v_add_f32_e32 v15, v15, v72
	v_add_f32_e32 v151, v65, v67
	v_add_f32_e32 v151, v151, v69
	v_add_f32_e32 v151, v151, v71
	v_add_f32_e32 v151, v151, v73
	v_mfma_f32_32x32x16_bf16 v[16:31], v[2:5], v[234:237], v[16:31]
	v_add_f32_e32 v15, v15, v74
	v_add_f32_e32 v15, v15, v76
	v_add_f32_e32 v15, v15, v78
	v_add_f32_e32 v151, v151, v75
	v_add_f32_e32 v151, v151, v77
	v_add_f32_e32 v151, v151, v79
	v_add_f32_e32 v0, v0, v14
	v_add_f32_e32 v15, v15, v151
	v_add_f32_e32 v0, v0, v15
	v_add_f32_e32 v149, v149, v0
	v_sub_f32_e32 v151, v142, v150
	s_waitcnt lgkmcnt(0)
	v_sub_f32_e32 v48, v151, v186
	v_sub_f32_e32 v49, v151, v187
	v_sub_f32_e32 v50, v151, v188
	v_sub_f32_e32 v51, v151, v189
	v_sub_f32_e32 v52, v151, v190
	v_sub_f32_e32 v53, v151, v191
	v_sub_f32_e32 v54, v151, v192
	v_sub_f32_e32 v55, v151, v193
	v_sub_f32_e32 v56, v151, v194
	v_sub_f32_e32 v57, v151, v195
	v_sub_f32_e32 v58, v151, v196
	v_sub_f32_e32 v59, v151, v197
	v_sub_f32_e32 v60, v151, v198
	v_sub_f32_e32 v61, v151, v199
	v_sub_f32_e32 v62, v151, v200
	v_sub_f32_e32 v63, v151, v201
	v_sub_f32_e32 v64, v151, v202
	v_sub_f32_e32 v65, v151, v203
	v_sub_f32_e32 v66, v151, v204
	v_sub_f32_e32 v67, v151, v205
	v_sub_f32_e32 v68, v151, v206
	v_sub_f32_e32 v69, v151, v207
	v_sub_f32_e32 v70, v151, v208
	v_sub_f32_e32 v71, v151, v209
	v_sub_f32_e32 v72, v151, v210
	v_sub_f32_e32 v73, v151, v211
	v_sub_f32_e32 v74, v151, v212
	v_sub_f32_e32 v75, v151, v213
	v_sub_f32_e32 v76, v151, v214
	v_sub_f32_e32 v77, v151, v215
	v_sub_f32_e32 v78, v151, v216
	v_sub_f32_e32 v79, v151, v217
.Lr1_noY:
	s_cmp_gt_i32 s22, s28
	s_cbranch_scc1 .Lr1_norescale
	s_add_i32 s6, s11, 0
	s_add_i32 s5, s6, 0x6800
	s_add_i32 s4, s15, s1
	s_cmp_eq_u32 s4, 1
	v_add_u32_e32 v0, s6, v143
	v_add_u32_e32 v14, s6, v144
	v_add_u32_e32 v15, s6, v145
	v_add_u32_e32 v151, s6, v146
	ds_read_b128 v[186:189], v0 offset:18432
	ds_read_b128 v[194:197], v14 offset:18432
	ds_read_b128 v[202:205], v15 offset:18432
	ds_read_b128 v[210:213], v151 offset:18432
	ds_read_b128 v[190:193], v0 offset:22528
	ds_read_b128 v[198:201], v14 offset:22528
	ds_read_b128 v[206:209], v15 offset:22528
	ds_read_b128 v[214:217], v151 offset:22528
	v_add_u32_e32 v0, s5, v147
	s_cbranch_scc0 .Lr1_have_init
	ds_read_b128 v[112:115], v148
	ds_read_b128 v[104:107], v148 offset:32
	ds_read_b128 v[108:111], v148 offset:64
	ds_read_b128 v[100:103], v148 offset:96
	ds_read_b128 v[96:99], v148 offset:128
	ds_read_b128 v[6:9], v148 offset:160
	ds_read_b128 v[10:13], v148 offset:192
	ds_read_b128 v[2:5], v148 offset:224
	v_sub_f32_e32 v151, v142, v150
	s_waitcnt lgkmcnt(0)
	v_sub_f32_e32 v48, v151, v112
	v_sub_f32_e32 v49, v151, v113
	v_sub_f32_e32 v50, v151, v114
	v_sub_f32_e32 v51, v151, v115
	v_sub_f32_e32 v52, v151, v104
	v_sub_f32_e32 v53, v151, v105
	v_sub_f32_e32 v54, v151, v106
	v_sub_f32_e32 v55, v151, v107
	v_sub_f32_e32 v56, v151, v108
	v_sub_f32_e32 v57, v151, v109
	v_sub_f32_e32 v58, v151, v110
	v_sub_f32_e32 v59, v151, v111
	v_sub_f32_e32 v60, v151, v100
	v_sub_f32_e32 v61, v151, v101
	v_sub_f32_e32 v62, v151, v102
	v_sub_f32_e32 v63, v151, v103
	v_sub_f32_e32 v64, v151, v96
	v_sub_f32_e32 v65, v151, v97
	v_sub_f32_e32 v66, v151, v98
	v_sub_f32_e32 v67, v151, v99
	v_sub_f32_e32 v68, v151, v6
	v_sub_f32_e32 v69, v151, v7
	v_sub_f32_e32 v70, v151, v8
	v_sub_f32_e32 v71, v151, v9
	v_sub_f32_e32 v72, v151, v10
	v_sub_f32_e32 v73, v151, v11
	v_sub_f32_e32 v74, v151, v12
	v_sub_f32_e32 v75, v151, v13
	v_sub_f32_e32 v76, v151, v2
	v_sub_f32_e32 v77, v151, v3
	v_sub_f32_e32 v78, v151, v4
	v_sub_f32_e32 v79, v151, v5
	s_nop 1

; template <int MODE>
; __device__ __forceinline__ void step64(St& S, const bf16x8 (&qf)[4], int t, int qpos0, bool diag, bool first, float cq, float cfar, const LAS float* tab,
;                                        const LAS unsigned char* buf, unsigned vaddr, int r32, int hi) {
;     ...
;     for (int r = 0; r < 16; ++r) { sa[r] = __builtin_amdgcn_exp2f(sa[r]); sb[r] = __builtin_amdgcn_exp2f(sb[r]); }
;     asm volatile("s_waitcnt lgkmcnt(0)" ::: "memory");
;     __builtin_amdgcn_sched_barrier(0);
;     u32x4 pa0, pa1, pb0, pb1;
;     pa0.x = pk2(sa[0], sa[1]); pa0.y = pk2(sa[2], sa[3]); pa0.z = pk2(sa[4], sa[5]); pa0.w = pk2(sa[6], sa[7]);
;     pa1.x = pk2(sa[8], sa[9]); pa1.y = pk2(sa[10], sa[11]); pa1.z = pk2(sa[12], sa[13]); pa1.w = pk2(sa[14], sa[15]);
;     pb0.x = pk2(sb[0], sb[1]); pb0.y = pk2(sb[2], sb[3]); pb0.z = pk2(sb[4], sb[5]); pb0.w = pk2(sb[6], sb[7]);
;     pb1.x = pk2(sb[8], sb[9]); pb1.y = pk2(sb[10], sb[11]); pb1.z = pk2(sb[12], sb[13]); pb1.w = pk2(sb[14], sb[15]);
;     ...
;     S.o0 = __builtin_amdgcn_mfma_f32_32x32x16_bf16(ATT_VF(0), ATT_PF(pa0), S.o0, 0, 0, 0);
;     S.o1 = __builtin_amdgcn_mfma_f32_32x32x16_bf16(ATT_VF(2), ATT_PF(pa0), S.o1, 0, 0, 0);
;     S.o0 = __builtin_amdgcn_mfma_f32_32x32x16_bf16(ATT_VF(1), ATT_PF(pa1), S.o0, 0, 0, 0);
;     S.o1 = __builtin_amdgcn_mfma_f32_32x32x16_bf16(ATT_VF(3), ATT_PF(pa1), S.o1, 0, 0, 0);
;     S.o0 = __builtin_amdgcn_mfma_f32_32x32x16_bf16(ATT_VF(4), ATT_PF(pb0), S.o0, 0, 0, 0);
;     S.o1 = __builtin_amdgcn_mfma_f32_32x32x16_bf16(ATT_VF(6), ATT_PF(pb0), S.o1, 0, 0, 0);
;     S.o0 = __builtin_amdgcn_mfma_f32_32x32x16_bf16(ATT_VF(5), ATT_PF(pb1), S.o0, 0, 0, 0);
;     S.o1 = __builtin_amdgcn_mfma_f32_32x32x16_bf16(ATT_VF(7), ATT_PF(pb1), S.o1, 0, 0, 0);
;     ...
;     float l0 = 0.f, l1 = 0.f, l2 = 0.f, l3 = 0.f;
; #pragma unroll
;     for (int r = 0; r < 16; r += 2) { l0 += sa[r]; l1 += sa[r + 1]; l2 += sb[r]; l3 += sb[r + 1]; }
;     S.l += (l0 + l1) + (l2 + l3);
; template <int MODE> ...
;     ...
;         if (more) asm volatile("s_waitcnt vmcnt(2) lgkmcnt(0)\n\ts_barrier" ::: "memory");
;         else      asm volatile("s_waitcnt vmcnt(0) lgkmcnt(0)\n\ts_barrier" ::: "memory");
;         const int sn = s0; s0 = s1; s1 = s2; s2 = sn;
;     }
.Lr1_norescale:
	s_and_b64 vcc, exec, s[24:25]
	s_cbranch_vccnz .Lr1_bar0
	s_waitcnt vmcnt(2) lgkmcnt(0)
	s_barrier
	s_branch .Lr1_ctl
.Lr1_bar0:
	s_waitcnt vmcnt(0) lgkmcnt(0)
	s_barrier
.Lr1_ctl:
	s_add_i32 s19, s19, 1
	v_lshl_add_u64 v[116:117], v[116:117], 0, s[26:27]
	v_lshl_add_u64 v[118:119], v[118:119], 0, s[26:27]
	s_cmp_lg_u32 s22, 0
	v_add_u32_e32 v148, 0xffffff00, v148
	s_cbranch_scc0 .Lr1_epi
	s_mov_b32 s1, s22
	s_mov_b32 s0, s10
	s_mov_b32 s10, s12
	s_mov_b32 s12, s11
	s_branch .Lr1_top
.Lr1_epi:
	s_waitcnt lgkmcnt(0)
	v_exp_f32_e32 v48, v48
	v_exp_f32_e32 v49, v49
	v_exp_f32_e32 v50, v50
	v_exp_f32_e32 v51, v51
	v_exp_f32_e32 v52, v52
	v_exp_f32_e32 v53, v53
	v_exp_f32_e32 v54, v54
	v_exp_f32_e32 v55, v55
	v_cvt_pk_bf16_f32 v152, v48, v49
	v_cvt_pk_bf16_f32 v153, v50, v51
	v_cvt_pk_bf16_f32 v154, v52, v53
	v_cvt_pk_bf16_f32 v155, v54, v55
	v_exp_f32_e32 v56, v56
	v_exp_f32_e32 v57, v57
	v_mfma_f32_32x32x16_bf16 v[32:47], v[112:115], v[152:155], v[32:47]
	v_exp_f32_e32 v58, v58
	v_exp_f32_e32 v59, v59
	v_exp_f32_e32 v60, v60
	v_exp_f32_e32 v61, v61
	v_exp_f32_e32 v62, v62
	v_exp_f32_e32 v63, v63
	v_mfma_f32_32x32x16_bf16 v[16:31], v[108:111], v[152:155], v[16:31]
	v_cvt_pk_bf16_f32 v156, v56, v57
	v_cvt_pk_bf16_f32 v157, v58, v59
	v_cvt_pk_bf16_f32 v158, v60, v61
	v_cvt_pk_bf16_f32 v159, v62, v63
	v_add_f32_e32 v0, v48, v50
	v_add_f32_e32 v0, v0, v52
	v_add_f32_e32 v14, v49, v51
	v_add_f32_e32 v14, v14, v53
	v_mfma_f32_32x32x16_bf16 v[32:47], v[104:107], v[156:159], v[32:47]
	v_exp_f32_e32 v64, v64
	v_exp_f32_e32 v65, v65
	v_exp_f32_e32 v66, v66
	v_exp_f32_e32 v67, v67
	v_exp_f32_e32 v68, v68
	v_exp_f32_e32 v69, v69
	v_exp_f32_e32 v70, v70
	v_exp_f32_e32 v71, v71
	v_mfma_f32_32x32x16_bf16 v[16:31], v[100:103], v[156:159], v[16:31]
	v_cvt_pk_bf16_f32 v160, v64, v65
	v_cvt_pk_bf16_f32 v161, v66, v67
	v_cvt_pk_bf16_f32 v162, v68, v69
	v_cvt_pk_bf16_f32 v163, v70, v71
	v_add_f32_e32 v0, v0, v54
	v_add_f32_e32 v0, v0, v56
	v_add_f32_e32 v14, v14, v55
	v_add_f32_e32 v14, v14, v57
	v_mfma_f32_32x32x16_bf16 v[32:47], v[96:99], v[160:163], v[32:47]
	v_exp_f32_e32 v72, v72
	v_exp_f32_e32 v73, v73
	v_exp_f32_e32 v74, v74
	v_exp_f32_e32 v75, v75
	v_exp_f32_e32 v76, v76
	v_exp_f32_e32 v77, v77
	v_exp_f32_e32 v78, v78
	v_exp_f32_e32 v79, v79
	v_mfma_f32_32x32x16_bf16 v[16:31], v[10:13], v[160:163], v[16:31]
	v_cvt_pk_bf16_f32 v234, v72, v73
	v_cvt_pk_bf16_f32 v235, v74, v75
	v_cvt_pk_bf16_f32 v236, v76, v77
	v_cvt_pk_bf16_f32 v237, v78, v79
	v_add_f32_e32 v0, v0, v58
	v_add_f32_e32 v0, v0, v60
	v_add_f32_e32 v0, v0, v62
	v_add_f32_e32 v14, v14, v59
	v_add_f32_e32 v14, v14, v61
	v_add_f32_e32 v14, v14, v63
	v_mfma_f32_32x32x16_bf16 v[32:47], v[6:9], v[234:237], v[32:47]
	v_add_f32_e32 v15, v64, v66
	v_add_f32_e32 v15, v15, v68
	v_add_f32_e32 v15, v15, v70
	v_add_f32_e32 v15, v15, v72
	v_add_f32_e32 v151, v65, v67
	v_add_f32_e32 v151, v151, v69
	v_add_f32_e32 v151, v151, v71
	v_add_f32_e32 v151, v151, v73
	v_mfma_f32_32x32x16_bf16 v[16:31], v[2:5], v[234:237], v[16:31]
	v_add_f32_e32 v15, v15, v74
	v_add_f32_e32 v15, v15, v76
	v_add_f32_e32 v15, v15, v78
	v_add_f32_e32 v151, v151, v75
	v_add_f32_e32 v151, v151, v77
	v_add_f32_e32 v151, v151, v79
	v_add_f32_e32 v0, v0, v14
	v_add_f32_e32 v15, v15, v151
	v_add_f32_e32 v0, v0, v15
	v_add_f32_e32 v149, v149, v0
	s_nop 7
	s_nop 4
	s_mov_b64 s[0:1], -1
	s_branch .LBB0_596
